# nt on the Fourier stage-1 output stores and the attention output stores (written once, read ms later) on top of k39
# baseline (speedup 1.0000x reference)
.LBB0_323:
	s_lshr_b32 s4, s8, 3
	s_cmpk_lt_i32 s8, 0x800
	s_cselect_b32 s31, s23, 0x800
	v_cvt_f32_u32_e32 v119, s31
	s_cselect_b32 s5, 0x7f, 15
	s_cselect_b32 s8, s18, 0x7ffff800
	s_cselect_b32 s30, s19, 0xffff8000
	s_cselect_b32 s2, s24, 0x400000
	s_and_b32 s28, s5, s4
	s_and_b32 s4, s8, s9
	s_add_i32 s8, s4, s30
	v_div_scale_f32 v123, s[4:5], v119, v119, 2.0
	v_rcp_f32_e32 v125, v123
	v_mul_lo_u32 v121, s28, v128
	s_add_i32 s31, s31, -1
	v_and_b32_e32 v121, s31, v121
	v_fma_f32 v127, -v123, v125, 1.0
	v_fmac_f32_e32 v125, v127, v125
	v_div_scale_f32 v127, vcc, 2.0, v119, 2.0
	v_mul_f32_e32 v151, v127, v125
	v_fma_f32 v152, -v123, v151, v127
	v_cvt_f32_u32_e32 v121, v121
	v_fmac_f32_e32 v151, v152, v125
	v_fma_f32 v123, -v123, v151, v127
	v_div_fmas_f32 v123, v123, v125, v151
	v_div_fixup_f32 v119, v123, v119, 2.0
	v_mul_f32_e32 v119, v119, v121
	v_mul_f32_e32 v121, 0.5, v119
	v_fract_f32_e32 v123, v121
	v_add_f32_e32 v123, v123, v123
	v_cmp_neq_f32_e64 vcc, |v121|, s1
	s_and_b32 s29, s29, 0x380
	s_nop 0
	v_cndmask_b32_e32 v121, 0, v123, vcc
	v_cmp_lt_f32_e32 vcc, 1.0, v119
	s_nop 1
	v_cndmask_b32_e32 v121, v119, v121, vcc
	v_add_f32_e32 v123, v121, v121
	v_rndne_f32_e32 v125, v123
	v_fmac_f32_e32 v121, -0.5, v125
	v_mul_f32_e32 v151, v121, v121
	v_fmamk_f32 v152, v151, 0x3e75aa41, v130
	v_fmaak_f32 v152, v151, v152, 0x40234736
	v_fmaak_f32 v152, v151, v152, 0xc0a55e0e
	v_mul_f32_e32 v153, v121, v151
	v_mul_f32_e32 v152, v153, v152
	v_cvt_i32_f32_e32 v127, v125
	v_fmac_f32_e32 v152, 0x40490fdb, v121
	v_fmamk_f32 v121, v151, 0x3d4be544, v131
	v_fmaak_f32 v121, v151, v121, 0xbfaad1da
	v_fmaak_f32 v121, v151, v121, 0x4081e0d3
	v_fmaak_f32 v121, v151, v121, 0xc09de9e6
	v_fma_f32 v121, v151, v121, 1.0
	v_and_b32_e32 v151, 1, v127
	v_and_b32_e32 v125, 2, v127
	v_cmp_eq_u32_e32 vcc, 0, v151
	v_mov_b32_e32 v123, v140
	v_cmp_eq_u32_e64 s[4:5], 0, v125
	v_cndmask_b32_e64 v151, -v152, v121, vcc
	v_cndmask_b32_e32 v121, v121, v152, vcc
	v_cndmask_b32_e64 v125, -v151, v151, s[4:5]
	v_cmp_lg_f32_e64 s[4:5], s1, v119
	ds_read_b64_tr_b16 v[152:153], v123 offset:0
	ds_read_b64_tr_b16 v[154:155], v123 offset:0x440
	s_nop 1
	v_cndmask_b32_e64 v119, v132, v125, s[4:5]
	v_lshlrev_b32_e32 v125, 30, v127
	v_bitop3_b32 v121, v125, v121, s10 bitop3:0x6c
	v_add_u32_e32 v125, 0x2200, v123
	ds_read_b64_tr_b16 v[156:157], v125 offset:0
	ds_read_b64_tr_b16 v[158:159], v125 offset:0x440
	v_add_u32_e32 v125, 0x4400, v123
	ds_read_b64_tr_b16 v[164:165], v125 offset:0
	ds_read_b64_tr_b16 v[166:167], v125 offset:0x440
	v_add_u32_e32 v125, 0x6600, v123
	ds_read_b64_tr_b16 v[168:169], v125 offset:0
	ds_read_b64_tr_b16 v[170:171], v125 offset:0x440
	v_add_u32_e32 v125, 0x8800, v123
	ds_read_b64_tr_b16 v[172:173], v125 offset:0
	ds_read_b64_tr_b16 v[174:175], v125 offset:0x440
	v_add_u32_e32 v125, 0xaa00, v123
	ds_read_b64_tr_b16 v[176:177], v125 offset:0
	ds_read_b64_tr_b16 v[178:179], v125 offset:0x440
	v_add_u32_e32 v125, 0xcc00, v123
	ds_read_b64_tr_b16 v[180:181], v125 offset:0
	ds_read_b64_tr_b16 v[182:183], v125 offset:0x440
	v_add_u32_e32 v125, 0xee00, v123
	ds_read_b64_tr_b16 v[184:185], v125 offset:0
	ds_read_b64_tr_b16 v[186:187], v125 offset:0x440
	s_waitcnt lgkmcnt(0)
	v_cndmask_b32_e64 v121, v132, v121, s[4:5]
	v_mfma_f32_16x16x32_bf16 v[188:191], v[152:155], v[2:5], 0
	v_mfma_f32_16x16x32_bf16 v[152:155], v[152:155], v[6:9], 0
	v_mfma_f32_16x16x32_bf16 v[188:191], v[156:159], v[10:13], v[188:191]
	v_mfma_f32_16x16x32_bf16 v[152:155], v[156:159], v[14:17], v[152:155]
	v_mfma_f32_16x16x32_bf16 v[156:159], v[164:167], v[18:21], v[188:191]
	v_mfma_f32_16x16x32_bf16 v[152:155], v[164:167], v[22:25], v[152:155]
	v_mfma_f32_16x16x32_bf16 v[156:159], v[168:171], v[26:29], v[156:159]
	v_mfma_f32_16x16x32_bf16 v[152:155], v[168:171], v[30:33], v[152:155]
	v_mfma_f32_16x16x32_bf16 v[156:159], v[172:175], v[34:37], v[156:159]
	v_mfma_f32_16x16x32_bf16 v[152:155], v[172:175], v[38:41], v[152:155]
	v_mfma_f32_16x16x32_bf16 v[156:159], v[176:179], v[42:45], v[156:159]
	v_mfma_f32_16x16x32_bf16 v[152:155], v[176:179], v[46:49], v[152:155]
	v_mfma_f32_16x16x32_bf16 v[156:159], v[180:183], v[50:53], v[156:159]
	v_mfma_f32_16x16x32_bf16 v[152:155], v[180:183], v[54:57], v[152:155]
	v_mfma_f32_16x16x32_bf16 v[156:159], v[184:187], v[58:61], v[156:159]
	v_mfma_f32_16x16x32_bf16 v[152:155], v[184:187], v[62:65], v[152:155]
	s_nop 6
	v_mul_f32_e32 v127, v121, v156
	v_mul_f32_e32 v125, v121, v152
	v_fma_f32 v127, v119, v152, -v127
	v_mul_f32_e32 v152, v121, v157
	v_fma_f32 v152, v119, v153, -v152
	v_fmac_f32_e32 v125, v119, v156
	v_mul_f32_e32 v156, 0x3db504f3, v152
	v_mul_f32_e32 v152, v121, v154
	v_fmac_f32_e32 v152, v119, v158
	v_mul_f32_e32 v151, v121, v153
	v_mul_f32_e32 v153, 0x3db504f3, v152
	v_mul_f32_e32 v152, v121, v158
	v_fma_f32 v152, v119, v154, -v152
	v_fmac_f32_e32 v151, v119, v157
	v_mul_f32_e32 v157, 0x3db504f3, v152
	v_mul_f32_e32 v152, v121, v155
	v_fmac_f32_e32 v152, v119, v159
	v_mul_f32_e32 v154, 0x3db504f3, v152
	v_mul_f32_e32 v152, v121, v159
	v_mul_f32_e32 v125, 0x3db504f3, v125
	v_fma_f32 v152, v119, v155, -v152
	v_mul_f32_e32 v151, 0x3db504f3, v151
	v_mul_f32_e32 v155, 0x3db504f3, v152
	v_cvt_pk_bf16_f32 v152, v125, v151
	v_cvt_pk_bf16_f32 v153, v153, v154
	v_add_u32_e32 v125, v141, v129
	v_mul_f32_e32 v127, 0x3db504f3, v127
	v_cvt_pk_bf16_f32 v154, v127, v156
	v_cvt_pk_bf16_f32 v155, v157, v155
	ds_write_b64 v125, v[152:153]
	ds_write_b64 v125, v[154:155] offset:4352
	v_add_u32_e32 v127, 32, v123
	ds_read_b64_tr_b16 v[152:153], v127 offset:0
	ds_read_b64_tr_b16 v[154:155], v127 offset:0x440
	v_add_u32_e32 v127, 0x2220, v123
	ds_read_b64_tr_b16 v[156:157], v127 offset:0
	ds_read_b64_tr_b16 v[158:159], v127 offset:0x440
	v_add_u32_e32 v127, 0x4420, v123
	ds_read_b64_tr_b16 v[164:165], v127 offset:0
	ds_read_b64_tr_b16 v[166:167], v127 offset:0x440
	v_add_u32_e32 v127, 0x6620, v123
	ds_read_b64_tr_b16 v[168:169], v127 offset:0
	ds_read_b64_tr_b16 v[170:171], v127 offset:0x440
	v_add_u32_e32 v127, 0x8820, v123
	ds_read_b64_tr_b16 v[172:173], v127 offset:0
	ds_read_b64_tr_b16 v[174:175], v127 offset:0x440
	v_add_u32_e32 v127, 0xaa20, v123
	ds_read_b64_tr_b16 v[176:177], v127 offset:0
	ds_read_b64_tr_b16 v[178:179], v127 offset:0x440
	v_add_u32_e32 v127, 0xcc20, v123
	ds_read_b64_tr_b16 v[180:181], v127 offset:0
	ds_read_b64_tr_b16 v[182:183], v127 offset:0x440
	v_add_u32_e32 v127, 0xee20, v123
	ds_read_b64_tr_b16 v[184:185], v127 offset:0
	ds_read_b64_tr_b16 v[186:187], v127 offset:0x440
	s_waitcnt lgkmcnt(0)
	v_mfma_f32_16x16x32_bf16 v[188:191], v[152:155], v[2:5], 0
	v_mfma_f32_16x16x32_bf16 v[152:155], v[152:155], v[6:9], 0
	v_mfma_f32_16x16x32_bf16 v[188:191], v[156:159], v[10:13], v[188:191]
	v_mfma_f32_16x16x32_bf16 v[152:155], v[156:159], v[14:17], v[152:155]
	v_mfma_f32_16x16x32_bf16 v[156:159], v[164:167], v[18:21], v[188:191]
	v_mfma_f32_16x16x32_bf16 v[152:155], v[164:167], v[22:25], v[152:155]
	v_mfma_f32_16x16x32_bf16 v[156:159], v[168:171], v[26:29], v[156:159]
	v_mfma_f32_16x16x32_bf16 v[152:155], v[168:171], v[30:33], v[152:155]
	v_mfma_f32_16x16x32_bf16 v[156:159], v[172:175], v[34:37], v[156:159]
	v_mfma_f32_16x16x32_bf16 v[152:155], v[172:175], v[38:41], v[152:155]
	v_mfma_f32_16x16x32_bf16 v[156:159], v[176:179], v[42:45], v[156:159]
	v_mfma_f32_16x16x32_bf16 v[152:155], v[176:179], v[46:49], v[152:155]
	v_mfma_f32_16x16x32_bf16 v[156:159], v[180:183], v[50:53], v[156:159]
	v_mfma_f32_16x16x32_bf16 v[152:155], v[180:183], v[54:57], v[152:155]
	v_mfma_f32_16x16x32_bf16 v[152:155], v[184:187], v[62:65], v[152:155]
	v_mfma_f32_16x16x32_bf16 v[156:159], v[184:187], v[58:61], v[156:159]
	s_nop 6
	v_mul_f32_e32 v127, v121, v152
	v_mul_f32_e32 v151, v121, v156
	v_fmac_f32_e32 v127, v119, v156
	v_fma_f32 v151, v119, v152, -v151
	v_mul_f32_e32 v152, v121, v153
	v_mul_f32_e32 v156, v121, v157
	v_fmac_f32_e32 v152, v119, v157
	v_fma_f32 v153, v119, v153, -v156
	v_mul_f32_e32 v157, v121, v158
	v_mul_f32_e32 v156, 0x3db504f3, v153
	v_mul_f32_e32 v153, v121, v154
	v_fma_f32 v154, v119, v154, -v157
	v_fmac_f32_e32 v153, v119, v158
	v_mul_f32_e32 v157, 0x3db504f3, v154
	v_mul_f32_e32 v154, v121, v155
	v_mul_f32_e32 v158, v121, v159
	v_mul_f32_e32 v152, 0x3db504f3, v152
	v_mul_f32_e32 v153, 0x3db504f3, v153
	v_fmac_f32_e32 v154, v119, v159
	v_fma_f32 v155, v119, v155, -v158
	v_mul_f32_e32 v127, 0x3db504f3, v127
	v_mul_f32_e32 v154, 0x3db504f3, v154
	v_mul_f32_e32 v155, 0x3db504f3, v155
	v_cvt_pk_bf16_f32 v152, v127, v152
	v_cvt_pk_bf16_f32 v153, v153, v154
	v_mul_f32_e32 v151, 0x3db504f3, v151
	v_cvt_pk_bf16_f32 v154, v151, v156
	v_cvt_pk_bf16_f32 v155, v157, v155
	ds_write_b64 v1, v[152:153]
	ds_write_b64 v1, v[154:155] offset:4352
	v_add_u32_e32 v127, 64, v123
	ds_read_b64_tr_b16 v[152:153], v127 offset:0
	ds_read_b64_tr_b16 v[154:155], v127 offset:0x440
	v_add_u32_e32 v127, 0x2240, v123
	ds_read_b64_tr_b16 v[156:157], v127 offset:0
	ds_read_b64_tr_b16 v[158:159], v127 offset:0x440
	v_add_u32_e32 v127, 0x4440, v123
	ds_read_b64_tr_b16 v[164:165], v127 offset:0
	ds_read_b64_tr_b16 v[166:167], v127 offset:0x440
	v_add_u32_e32 v127, 0x6640, v123
	ds_read_b64_tr_b16 v[168:169], v127 offset:0
	ds_read_b64_tr_b16 v[170:171], v127 offset:0x440
	v_add_u32_e32 v127, 0x8840, v123
	ds_read_b64_tr_b16 v[172:173], v127 offset:0
	ds_read_b64_tr_b16 v[174:175], v127 offset:0x440
	v_add_u32_e32 v127, 0xaa40, v123
	ds_read_b64_tr_b16 v[176:177], v127 offset:0
	ds_read_b64_tr_b16 v[178:179], v127 offset:0x440
	v_add_u32_e32 v127, 0xcc40, v123
	ds_read_b64_tr_b16 v[180:181], v127 offset:0
	ds_read_b64_tr_b16 v[182:183], v127 offset:0x440
	v_add_u32_e32 v127, 0xee40, v123
	ds_read_b64_tr_b16 v[184:185], v127 offset:0
	ds_read_b64_tr_b16 v[186:187], v127 offset:0x440
	s_waitcnt lgkmcnt(0)
	v_mfma_f32_16x16x32_bf16 v[188:191], v[152:155], v[2:5], 0
	v_mfma_f32_16x16x32_bf16 v[152:155], v[152:155], v[6:9], 0
	v_mfma_f32_16x16x32_bf16 v[188:191], v[156:159], v[10:13], v[188:191]
	v_mfma_f32_16x16x32_bf16 v[152:155], v[156:159], v[14:17], v[152:155]
	v_mfma_f32_16x16x32_bf16 v[156:159], v[164:167], v[18:21], v[188:191]
	v_mfma_f32_16x16x32_bf16 v[152:155], v[164:167], v[22:25], v[152:155]
	v_mfma_f32_16x16x32_bf16 v[156:159], v[168:171], v[26:29], v[156:159]
	v_mfma_f32_16x16x32_bf16 v[152:155], v[168:171], v[30:33], v[152:155]
	v_mfma_f32_16x16x32_bf16 v[156:159], v[172:175], v[34:37], v[156:159]
	v_mfma_f32_16x16x32_bf16 v[152:155], v[172:175], v[38:41], v[152:155]
	v_mfma_f32_16x16x32_bf16 v[156:159], v[176:179], v[42:45], v[156:159]
	v_mfma_f32_16x16x32_bf16 v[152:155], v[176:179], v[46:49], v[152:155]
	v_mfma_f32_16x16x32_bf16 v[156:159], v[180:183], v[50:53], v[156:159]
	v_mfma_f32_16x16x32_bf16 v[152:155], v[180:183], v[54:57], v[152:155]
	v_mfma_f32_16x16x32_bf16 v[152:155], v[184:187], v[62:65], v[152:155]
	v_mfma_f32_16x16x32_bf16 v[156:159], v[184:187], v[58:61], v[156:159]
	s_nop 6
	v_mul_f32_e32 v127, v121, v152
	v_mul_f32_e32 v151, v121, v156
	v_fmac_f32_e32 v127, v119, v156
	v_fma_f32 v151, v119, v152, -v151
	v_mul_f32_e32 v152, v121, v153
	v_mul_f32_e32 v156, v121, v157
	v_fmac_f32_e32 v152, v119, v157
	v_fma_f32 v153, v119, v153, -v156
	v_mul_f32_e32 v157, v121, v158
	v_mul_f32_e32 v156, 0x3db504f3, v153
	v_mul_f32_e32 v153, v121, v154
	v_fma_f32 v154, v119, v154, -v157
	v_fmac_f32_e32 v153, v119, v158
	v_mul_f32_e32 v157, 0x3db504f3, v154
	v_mul_f32_e32 v154, v121, v155
	v_mul_f32_e32 v158, v121, v159
	v_mul_f32_e32 v152, 0x3db504f3, v152
	v_mul_f32_e32 v153, 0x3db504f3, v153
	v_fmac_f32_e32 v154, v119, v159
	v_fma_f32 v155, v119, v155, -v158
	v_mul_f32_e32 v127, 0x3db504f3, v127
	v_mul_f32_e32 v154, 0x3db504f3, v154
	v_mul_f32_e32 v155, 0x3db504f3, v155
	v_cvt_pk_bf16_f32 v152, v127, v152
	v_cvt_pk_bf16_f32 v153, v153, v154
	v_mul_f32_e32 v151, 0x3db504f3, v151
	v_cvt_pk_bf16_f32 v154, v151, v156
	v_cvt_pk_bf16_f32 v155, v157, v155
	ds_write_b64 v145, v[152:153]
	ds_write_b64 v145, v[154:155] offset:4352
	v_add_u32_e32 v127, 0x60, v123
	ds_read_b64_tr_b16 v[152:153], v127 offset:0
	ds_read_b64_tr_b16 v[154:155], v127 offset:0x440
	v_add_u32_e32 v127, 0x2260, v123
	ds_read_b64_tr_b16 v[156:157], v127 offset:0
	ds_read_b64_tr_b16 v[158:159], v127 offset:0x440
	v_add_u32_e32 v127, 0x4460, v123
	ds_read_b64_tr_b16 v[164:165], v127 offset:0
	ds_read_b64_tr_b16 v[166:167], v127 offset:0x440
	v_add_u32_e32 v127, 0x6660, v123
	ds_read_b64_tr_b16 v[168:169], v127 offset:0
	ds_read_b64_tr_b16 v[170:171], v127 offset:0x440
	v_add_u32_e32 v127, 0x8860, v123
	ds_read_b64_tr_b16 v[172:173], v127 offset:0
	ds_read_b64_tr_b16 v[174:175], v127 offset:0x440
	v_add_u32_e32 v127, 0xaa60, v123
	ds_read_b64_tr_b16 v[176:177], v127 offset:0
	ds_read_b64_tr_b16 v[178:179], v127 offset:0x440
	v_add_u32_e32 v127, 0xcc60, v123
	ds_read_b64_tr_b16 v[180:181], v127 offset:0
	ds_read_b64_tr_b16 v[182:183], v127 offset:0x440
	v_add_u32_e32 v127, 0xee60, v123
	ds_read_b64_tr_b16 v[184:185], v127 offset:0
	ds_read_b64_tr_b16 v[186:187], v127 offset:0x440
	s_waitcnt lgkmcnt(0)
	v_mfma_f32_16x16x32_bf16 v[188:191], v[152:155], v[2:5], 0
	v_mfma_f32_16x16x32_bf16 v[152:155], v[152:155], v[6:9], 0
	v_mfma_f32_16x16x32_bf16 v[188:191], v[156:159], v[10:13], v[188:191]
	v_mfma_f32_16x16x32_bf16 v[152:155], v[156:159], v[14:17], v[152:155]
	v_mfma_f32_16x16x32_bf16 v[156:159], v[164:167], v[18:21], v[188:191]
	v_mfma_f32_16x16x32_bf16 v[152:155], v[164:167], v[22:25], v[152:155]
	v_mfma_f32_16x16x32_bf16 v[156:159], v[168:171], v[26:29], v[156:159]
	v_mfma_f32_16x16x32_bf16 v[152:155], v[168:171], v[30:33], v[152:155]
	v_mfma_f32_16x16x32_bf16 v[156:159], v[172:175], v[34:37], v[156:159]
	v_mfma_f32_16x16x32_bf16 v[152:155], v[172:175], v[38:41], v[152:155]
	v_mfma_f32_16x16x32_bf16 v[156:159], v[176:179], v[42:45], v[156:159]
	v_mfma_f32_16x16x32_bf16 v[152:155], v[176:179], v[46:49], v[152:155]
	v_mfma_f32_16x16x32_bf16 v[156:159], v[180:183], v[50:53], v[156:159]
	v_mfma_f32_16x16x32_bf16 v[152:155], v[180:183], v[54:57], v[152:155]
	v_mfma_f32_16x16x32_bf16 v[152:155], v[184:187], v[62:65], v[152:155]
	v_mfma_f32_16x16x32_bf16 v[156:159], v[184:187], v[58:61], v[156:159]
	s_nop 6
	v_mul_f32_e32 v127, v121, v152
	v_mul_f32_e32 v151, v121, v156
	v_fmac_f32_e32 v127, v119, v156
	v_fma_f32 v151, v119, v152, -v151
	v_mul_f32_e32 v152, v121, v153
	v_mul_f32_e32 v156, v121, v157
	v_fmac_f32_e32 v152, v119, v157
	v_fma_f32 v153, v119, v153, -v156
	v_mul_f32_e32 v157, v121, v158
	v_mul_f32_e32 v156, 0x3db504f3, v153
	v_mul_f32_e32 v153, v121, v154
	v_fma_f32 v154, v119, v154, -v157
	v_fmac_f32_e32 v153, v119, v158
	v_mul_f32_e32 v157, 0x3db504f3, v154
	v_mul_f32_e32 v154, v121, v155
	v_mul_f32_e32 v158, v121, v159
	v_mul_f32_e32 v152, 0x3db504f3, v152
	v_mul_f32_e32 v153, 0x3db504f3, v153
	v_fmac_f32_e32 v154, v119, v159
	v_fma_f32 v155, v119, v155, -v158
	v_mul_f32_e32 v127, 0x3db504f3, v127
	v_mul_f32_e32 v154, 0x3db504f3, v154
	v_mul_f32_e32 v155, 0x3db504f3, v155
	v_cvt_pk_bf16_f32 v152, v127, v152
	v_cvt_pk_bf16_f32 v153, v153, v154
	v_mul_f32_e32 v151, 0x3db504f3, v151
	v_cvt_pk_bf16_f32 v154, v151, v156
	v_cvt_pk_bf16_f32 v155, v157, v155
	ds_write_b64 v146, v[152:153]
	ds_write_b64 v146, v[154:155] offset:4352
	v_add_u32_e32 v127, 0x80, v123
	ds_read_b64_tr_b16 v[152:153], v127 offset:0
	ds_read_b64_tr_b16 v[154:155], v127 offset:0x440
	v_add_u32_e32 v127, 0x2280, v123
	ds_read_b64_tr_b16 v[156:157], v127 offset:0
	ds_read_b64_tr_b16 v[158:159], v127 offset:0x440
	v_add_u32_e32 v127, 0x4480, v123
	ds_read_b64_tr_b16 v[164:165], v127 offset:0
	ds_read_b64_tr_b16 v[166:167], v127 offset:0x440
	v_add_u32_e32 v127, 0x6680, v123
	ds_read_b64_tr_b16 v[168:169], v127 offset:0
	ds_read_b64_tr_b16 v[170:171], v127 offset:0x440
	v_add_u32_e32 v127, 0x8880, v123
	ds_read_b64_tr_b16 v[172:173], v127 offset:0
	ds_read_b64_tr_b16 v[174:175], v127 offset:0x440
	v_add_u32_e32 v127, 0xaa80, v123
	ds_read_b64_tr_b16 v[176:177], v127 offset:0
	ds_read_b64_tr_b16 v[178:179], v127 offset:0x440
	v_add_u32_e32 v127, 0xcc80, v123
	ds_read_b64_tr_b16 v[180:181], v127 offset:0
	ds_read_b64_tr_b16 v[182:183], v127 offset:0x440
	v_add_u32_e32 v127, 0xee80, v123
	ds_read_b64_tr_b16 v[184:185], v127 offset:0
	ds_read_b64_tr_b16 v[186:187], v127 offset:0x440
	s_waitcnt lgkmcnt(0)
	v_mfma_f32_16x16x32_bf16 v[188:191], v[152:155], v[2:5], 0
	v_mfma_f32_16x16x32_bf16 v[152:155], v[152:155], v[6:9], 0
	v_mfma_f32_16x16x32_bf16 v[188:191], v[156:159], v[10:13], v[188:191]
	v_mfma_f32_16x16x32_bf16 v[152:155], v[156:159], v[14:17], v[152:155]
	v_mfma_f32_16x16x32_bf16 v[156:159], v[164:167], v[18:21], v[188:191]
	v_mfma_f32_16x16x32_bf16 v[152:155], v[164:167], v[22:25], v[152:155]
	v_mfma_f32_16x16x32_bf16 v[156:159], v[168:171], v[26:29], v[156:159]
	v_mfma_f32_16x16x32_bf16 v[152:155], v[168:171], v[30:33], v[152:155]
	v_mfma_f32_16x16x32_bf16 v[156:159], v[172:175], v[34:37], v[156:159]
	v_mfma_f32_16x16x32_bf16 v[152:155], v[172:175], v[38:41], v[152:155]
	v_mfma_f32_16x16x32_bf16 v[156:159], v[176:179], v[42:45], v[156:159]
	v_mfma_f32_16x16x32_bf16 v[152:155], v[176:179], v[46:49], v[152:155]
	v_mfma_f32_16x16x32_bf16 v[156:159], v[180:183], v[50:53], v[156:159]
	v_mfma_f32_16x16x32_bf16 v[152:155], v[180:183], v[54:57], v[152:155]
	v_mfma_f32_16x16x32_bf16 v[152:155], v[184:187], v[62:65], v[152:155]
	v_mfma_f32_16x16x32_bf16 v[156:159], v[184:187], v[58:61], v[156:159]
	s_nop 6
	v_mul_f32_e32 v127, v121, v152
	v_mul_f32_e32 v151, v121, v156
	v_fmac_f32_e32 v127, v119, v156
	v_fma_f32 v151, v119, v152, -v151
	v_mul_f32_e32 v152, v121, v153
	v_mul_f32_e32 v156, v121, v157
	v_fmac_f32_e32 v152, v119, v157
	v_fma_f32 v153, v119, v153, -v156
	v_mul_f32_e32 v157, v121, v158
	v_mul_f32_e32 v156, 0x3db504f3, v153
	v_mul_f32_e32 v153, v121, v154
	v_fma_f32 v154, v119, v154, -v157
	v_fmac_f32_e32 v153, v119, v158
	v_mul_f32_e32 v157, 0x3db504f3, v154
	v_mul_f32_e32 v154, v121, v155
	v_mul_f32_e32 v158, v121, v159
	v_mul_f32_e32 v152, 0x3db504f3, v152
	v_mul_f32_e32 v153, 0x3db504f3, v153
	v_fmac_f32_e32 v154, v119, v159
	v_fma_f32 v155, v119, v155, -v158
	v_mul_f32_e32 v127, 0x3db504f3, v127
	v_mul_f32_e32 v154, 0x3db504f3, v154
	v_mul_f32_e32 v155, 0x3db504f3, v155
	v_cvt_pk_bf16_f32 v152, v127, v152
	v_cvt_pk_bf16_f32 v153, v153, v154
	v_mul_f32_e32 v151, 0x3db504f3, v151
	v_cvt_pk_bf16_f32 v154, v151, v156
	v_cvt_pk_bf16_f32 v155, v157, v155
	ds_write_b64 v125, v[152:153] offset:128
	ds_write_b64 v125, v[154:155] offset:4480
	v_add_u32_e32 v127, 0xa0, v123
	ds_read_b64_tr_b16 v[152:153], v127 offset:0
	ds_read_b64_tr_b16 v[154:155], v127 offset:0x440
	v_add_u32_e32 v127, 0x22a0, v123
	ds_read_b64_tr_b16 v[156:157], v127 offset:0
	ds_read_b64_tr_b16 v[158:159], v127 offset:0x440
	v_add_u32_e32 v127, 0x44a0, v123
	ds_read_b64_tr_b16 v[164:165], v127 offset:0
	ds_read_b64_tr_b16 v[166:167], v127 offset:0x440
	v_add_u32_e32 v127, 0x66a0, v123
	ds_read_b64_tr_b16 v[168:169], v127 offset:0
	ds_read_b64_tr_b16 v[170:171], v127 offset:0x440
	v_add_u32_e32 v127, 0x88a0, v123
	ds_read_b64_tr_b16 v[172:173], v127 offset:0
	ds_read_b64_tr_b16 v[174:175], v127 offset:0x440
	v_add_u32_e32 v127, 0xaaa0, v123
	ds_read_b64_tr_b16 v[176:177], v127 offset:0
	ds_read_b64_tr_b16 v[178:179], v127 offset:0x440
	v_add_u32_e32 v127, 0xcca0, v123
	ds_read_b64_tr_b16 v[180:181], v127 offset:0
	ds_read_b64_tr_b16 v[182:183], v127 offset:0x440
	v_add_u32_e32 v127, 0xeea0, v123
	ds_read_b64_tr_b16 v[184:185], v127 offset:0
	ds_read_b64_tr_b16 v[186:187], v127 offset:0x440
	s_waitcnt lgkmcnt(0)
	v_mfma_f32_16x16x32_bf16 v[188:191], v[152:155], v[2:5], 0
	v_mfma_f32_16x16x32_bf16 v[152:155], v[152:155], v[6:9], 0
	v_mfma_f32_16x16x32_bf16 v[188:191], v[156:159], v[10:13], v[188:191]
	v_mfma_f32_16x16x32_bf16 v[152:155], v[156:159], v[14:17], v[152:155]
	v_mfma_f32_16x16x32_bf16 v[156:159], v[164:167], v[18:21], v[188:191]
	v_mfma_f32_16x16x32_bf16 v[152:155], v[164:167], v[22:25], v[152:155]
	v_mfma_f32_16x16x32_bf16 v[156:159], v[168:171], v[26:29], v[156:159]
	v_mfma_f32_16x16x32_bf16 v[152:155], v[168:171], v[30:33], v[152:155]
	v_mfma_f32_16x16x32_bf16 v[156:159], v[172:175], v[34:37], v[156:159]
	v_mfma_f32_16x16x32_bf16 v[152:155], v[172:175], v[38:41], v[152:155]
	v_mfma_f32_16x16x32_bf16 v[156:159], v[176:179], v[42:45], v[156:159]
	v_mfma_f32_16x16x32_bf16 v[152:155], v[176:179], v[46:49], v[152:155]
	v_mfma_f32_16x16x32_bf16 v[156:159], v[180:183], v[50:53], v[156:159]
	v_mfma_f32_16x16x32_bf16 v[152:155], v[180:183], v[54:57], v[152:155]
	v_mfma_f32_16x16x32_bf16 v[152:155], v[184:187], v[62:65], v[152:155]
	v_mfma_f32_16x16x32_bf16 v[156:159], v[184:187], v[58:61], v[156:159]
	s_nop 6
	v_mul_f32_e32 v127, v121, v152
	v_mul_f32_e32 v151, v121, v156
	v_fmac_f32_e32 v127, v119, v156
	v_fma_f32 v151, v119, v152, -v151
	v_mul_f32_e32 v152, v121, v153
	v_mul_f32_e32 v156, v121, v157
	v_fmac_f32_e32 v152, v119, v157
	v_fma_f32 v153, v119, v153, -v156
	v_mul_f32_e32 v157, v121, v158
	v_mul_f32_e32 v156, 0x3db504f3, v153
	v_mul_f32_e32 v153, v121, v154
	v_fma_f32 v154, v119, v154, -v157
	v_fmac_f32_e32 v153, v119, v158
	v_mul_f32_e32 v157, 0x3db504f3, v154
	v_mul_f32_e32 v154, v121, v155
	v_mul_f32_e32 v158, v121, v159
	v_mul_f32_e32 v152, 0x3db504f3, v152
	v_mul_f32_e32 v153, 0x3db504f3, v153
	v_fmac_f32_e32 v154, v119, v159
	v_fma_f32 v155, v119, v155, -v158
	v_mul_f32_e32 v127, 0x3db504f3, v127
	v_mul_f32_e32 v154, 0x3db504f3, v154
	v_mul_f32_e32 v155, 0x3db504f3, v155
	v_cvt_pk_bf16_f32 v152, v127, v152
	v_cvt_pk_bf16_f32 v153, v153, v154
	v_mul_f32_e32 v151, 0x3db504f3, v151
	v_cvt_pk_bf16_f32 v154, v151, v156
	v_cvt_pk_bf16_f32 v155, v157, v155
	ds_write_b64 v125, v[152:153] offset:160
	ds_write_b64 v125, v[154:155] offset:4512
	v_add_u32_e32 v127, 0xc0, v123
	ds_read_b64_tr_b16 v[152:153], v127 offset:0
	ds_read_b64_tr_b16 v[154:155], v127 offset:0x440
	v_add_u32_e32 v127, 0x22c0, v123
	ds_read_b64_tr_b16 v[156:157], v127 offset:0
	ds_read_b64_tr_b16 v[158:159], v127 offset:0x440
	v_add_u32_e32 v127, 0x44c0, v123
	ds_read_b64_tr_b16 v[164:165], v127 offset:0
	ds_read_b64_tr_b16 v[166:167], v127 offset:0x440
	v_add_u32_e32 v127, 0x66c0, v123
	ds_read_b64_tr_b16 v[168:169], v127 offset:0
	ds_read_b64_tr_b16 v[170:171], v127 offset:0x440
	v_add_u32_e32 v127, 0x88c0, v123
	ds_read_b64_tr_b16 v[172:173], v127 offset:0
	ds_read_b64_tr_b16 v[174:175], v127 offset:0x440
	v_add_u32_e32 v127, 0xaac0, v123
	ds_read_b64_tr_b16 v[176:177], v127 offset:0
	ds_read_b64_tr_b16 v[178:179], v127 offset:0x440
	v_add_u32_e32 v127, 0xccc0, v123
	ds_read_b64_tr_b16 v[180:181], v127 offset:0
	ds_read_b64_tr_b16 v[182:183], v127 offset:0x440
	v_add_u32_e32 v127, 0xeec0, v123
	ds_read_b64_tr_b16 v[184:185], v127 offset:0
	ds_read_b64_tr_b16 v[186:187], v127 offset:0x440
	s_waitcnt lgkmcnt(0)
	v_mfma_f32_16x16x32_bf16 v[188:191], v[152:155], v[2:5], 0
	v_mfma_f32_16x16x32_bf16 v[152:155], v[152:155], v[6:9], 0
	v_mfma_f32_16x16x32_bf16 v[188:191], v[156:159], v[10:13], v[188:191]
	v_mfma_f32_16x16x32_bf16 v[152:155], v[156:159], v[14:17], v[152:155]
	v_mfma_f32_16x16x32_bf16 v[156:159], v[164:167], v[18:21], v[188:191]
	v_mfma_f32_16x16x32_bf16 v[152:155], v[164:167], v[22:25], v[152:155]
	v_mfma_f32_16x16x32_bf16 v[156:159], v[168:171], v[26:29], v[156:159]
	v_mfma_f32_16x16x32_bf16 v[152:155], v[168:171], v[30:33], v[152:155]
	v_mfma_f32_16x16x32_bf16 v[156:159], v[172:175], v[34:37], v[156:159]
	v_mfma_f32_16x16x32_bf16 v[152:155], v[172:175], v[38:41], v[152:155]
	v_mfma_f32_16x16x32_bf16 v[156:159], v[176:179], v[42:45], v[156:159]
	v_mfma_f32_16x16x32_bf16 v[152:155], v[176:179], v[46:49], v[152:155]
	v_mfma_f32_16x16x32_bf16 v[156:159], v[180:183], v[50:53], v[156:159]
	v_mfma_f32_16x16x32_bf16 v[152:155], v[180:183], v[54:57], v[152:155]
	v_mfma_f32_16x16x32_bf16 v[152:155], v[184:187], v[62:65], v[152:155]
	v_mfma_f32_16x16x32_bf16 v[156:159], v[184:187], v[58:61], v[156:159]
	s_nop 6
	v_mul_f32_e32 v127, v121, v152
	v_mul_f32_e32 v151, v121, v156
	v_fmac_f32_e32 v127, v119, v156
	v_fma_f32 v151, v119, v152, -v151
	v_mul_f32_e32 v152, v121, v153
	v_mul_f32_e32 v156, v121, v157
	v_fmac_f32_e32 v152, v119, v157
	v_fma_f32 v153, v119, v153, -v156
	v_mul_f32_e32 v157, v121, v158
	v_mul_f32_e32 v156, 0x3db504f3, v153
	v_mul_f32_e32 v153, v121, v154
	v_fma_f32 v154, v119, v154, -v157
	v_fmac_f32_e32 v153, v119, v158
	v_mul_f32_e32 v157, 0x3db504f3, v154
	v_mul_f32_e32 v154, v121, v155
	v_mul_f32_e32 v158, v121, v159
	v_mul_f32_e32 v152, 0x3db504f3, v152
	v_mul_f32_e32 v153, 0x3db504f3, v153
	v_fmac_f32_e32 v154, v119, v159
	v_fma_f32 v155, v119, v155, -v158
	v_mul_f32_e32 v127, 0x3db504f3, v127
	v_mul_f32_e32 v154, 0x3db504f3, v154
	v_mul_f32_e32 v155, 0x3db504f3, v155
	v_cvt_pk_bf16_f32 v152, v127, v152
	v_cvt_pk_bf16_f32 v153, v153, v154
	v_mul_f32_e32 v151, 0x3db504f3, v151
	v_cvt_pk_bf16_f32 v154, v151, v156
	v_cvt_pk_bf16_f32 v155, v157, v155
	ds_write_b64 v125, v[152:153] offset:192
	ds_write_b64 v125, v[154:155] offset:4544
	v_add_u32_e32 v127, 0xe0, v123
	ds_read_b64_tr_b16 v[152:153], v127 offset:0
	ds_read_b64_tr_b16 v[154:155], v127 offset:0x440
	v_add_u32_e32 v127, 0x22e0, v123
	ds_read_b64_tr_b16 v[156:157], v127 offset:0
	ds_read_b64_tr_b16 v[158:159], v127 offset:0x440
	v_add_u32_e32 v127, 0x44e0, v123
	ds_read_b64_tr_b16 v[164:165], v127 offset:0
	ds_read_b64_tr_b16 v[166:167], v127 offset:0x440
	v_add_u32_e32 v127, 0x66e0, v123
	ds_read_b64_tr_b16 v[168:169], v127 offset:0
	ds_read_b64_tr_b16 v[170:171], v127 offset:0x440
	v_add_u32_e32 v127, 0x88e0, v123
	ds_read_b64_tr_b16 v[172:173], v127 offset:0
	ds_read_b64_tr_b16 v[174:175], v127 offset:0x440
	v_add_u32_e32 v127, 0xaae0, v123
	ds_read_b64_tr_b16 v[176:177], v127 offset:0
	ds_read_b64_tr_b16 v[178:179], v127 offset:0x440
	v_add_u32_e32 v127, 0xcce0, v123
	ds_read_b64_tr_b16 v[180:181], v127 offset:0
	ds_read_b64_tr_b16 v[182:183], v127 offset:0x440
	v_add_u32_e32 v123, 0xeee0, v123
	ds_read_b64_tr_b16 v[184:185], v123 offset:0
	ds_read_b64_tr_b16 v[186:187], v123 offset:0x440
	s_waitcnt lgkmcnt(0)
	v_mfma_f32_16x16x32_bf16 v[188:191], v[152:155], v[2:5], 0
	s_ashr_i32 s9, s8, 31
	s_lshl_b64 s[4:5], s[8:9], 12
	s_add_u32 s4, s12, s4
	v_mfma_f32_16x16x32_bf16 v[152:155], v[152:155], v[6:9], 0
	s_addc_u32 s5, s13, s5
	s_lshl_b32 s8, s28, 18
	s_add_u32 s4, s4, s8
	v_mfma_f32_16x16x32_bf16 v[188:191], v[156:159], v[10:13], v[188:191]
	s_addc_u32 s5, s5, 0
	s_andn2_b64 vcc, exec, s[6:7]
	s_mov_b32 s9, s26
	v_mfma_f32_16x16x32_bf16 v[152:155], v[156:159], v[14:17], v[152:155]
	s_mov_b32 s8, s25
	v_mfma_f32_16x16x32_bf16 v[156:159], v[164:167], v[18:21], v[188:191]
	v_mfma_f32_16x16x32_bf16 v[152:155], v[164:167], v[22:25], v[152:155]
	v_mfma_f32_16x16x32_bf16 v[156:159], v[168:171], v[26:29], v[156:159]
	v_mfma_f32_16x16x32_bf16 v[152:155], v[168:171], v[30:33], v[152:155]
	v_mfma_f32_16x16x32_bf16 v[156:159], v[172:175], v[34:37], v[156:159]
	v_mfma_f32_16x16x32_bf16 v[152:155], v[172:175], v[38:41], v[152:155]
	v_mfma_f32_16x16x32_bf16 v[156:159], v[176:179], v[42:45], v[156:159]
	v_mfma_f32_16x16x32_bf16 v[152:155], v[176:179], v[46:49], v[152:155]
	v_mfma_f32_16x16x32_bf16 v[156:159], v[180:183], v[50:53], v[156:159]
	v_mfma_f32_16x16x32_bf16 v[152:155], v[180:183], v[54:57], v[152:155]
	v_mfma_f32_16x16x32_bf16 v[156:159], v[184:187], v[58:61], v[156:159]
	v_mfma_f32_16x16x32_bf16 v[152:155], v[184:187], v[62:65], v[152:155]
	s_nop 6
	v_mul_f32_e32 v127, v121, v156
	v_mul_f32_e32 v123, v121, v152
	v_fma_f32 v127, v119, v152, -v127
	v_mul_f32_e32 v152, v121, v157
	v_fma_f32 v152, v119, v153, -v152
	v_fmac_f32_e32 v123, v119, v156
	v_mul_f32_e32 v156, 0x3db504f3, v152
	v_mul_f32_e32 v152, v121, v154
	v_fmac_f32_e32 v152, v119, v158
	v_mul_f32_e32 v151, v121, v153
	v_mul_f32_e32 v153, 0x3db504f3, v152
	v_mul_f32_e32 v152, v121, v158
	v_fma_f32 v152, v119, v154, -v152
	v_fmac_f32_e32 v151, v119, v157
	v_mul_f32_e32 v157, 0x3db504f3, v152
	v_mul_f32_e32 v152, v121, v155
	v_fmac_f32_e32 v152, v119, v159
	v_mul_f32_e32 v121, v121, v159
	v_mul_f32_e32 v123, 0x3db504f3, v123
	v_mul_f32_e32 v151, 0x3db504f3, v151
	v_mul_f32_e32 v154, 0x3db504f3, v152
	v_fma_f32 v119, v119, v155, -v121
	v_cvt_pk_bf16_f32 v152, v123, v151
	v_cvt_pk_bf16_f32 v153, v153, v154
	v_mul_f32_e32 v127, 0x3db504f3, v127
	v_mul_f32_e32 v119, 0x3db504f3, v119
	v_cvt_pk_bf16_f32 v154, v127, v156
	v_cvt_pk_bf16_f32 v155, v157, v119
	ds_write_b64 v125, v[152:153] offset:224
	ds_write_b64 v125, v[154:155] offset:4576
	v_lshl_add_u64 v[152:153], s[4:5], 0, v[98:99]
	s_lshl_b32 s4, s29, 1
	s_mov_b32 s5, s3
	v_add_u32_e32 v121, v143, v142
	v_lshl_add_u64 v[160:161], v[152:153], 0, s[4:5]
	ds_read_b128 v[152:155], v121
	v_lshl_add_u64 v[156:157], v[160:161], 0, v[116:117]
	v_mov_b32_e32 v119, v117
	v_lshl_add_u64 v[164:165], v[156:157], 0, v[118:119]
	ds_read_b128 v[156:159], v121 offset:4352
	s_waitcnt lgkmcnt(1)
	global_store_dwordx4 v[164:165], v[152:155], off nt
	ds_read_b128 v[152:155], v147
	v_mov_b32_e32 v121, v117
	v_lshl_add_u64 v[164:165], v[160:161], 0, v[120:121]
	v_lshl_add_u64 v[168:169], v[164:165], 0, v[118:119]
	ds_read_b128 v[164:167], v147 offset:4352
	s_waitcnt lgkmcnt(1)
	global_store_dwordx4 v[168:169], v[152:155], off nt
	ds_read_b128 v[152:155], v148
	v_mov_b32_e32 v123, v117
	v_lshl_add_u64 v[168:169], v[160:161], 0, v[122:123]
	v_lshl_add_u64 v[172:173], v[168:169], 0, v[118:119]
	ds_read_b128 v[168:171], v148 offset:4352
	s_waitcnt lgkmcnt(1)
	global_store_dwordx4 v[172:173], v[152:155], off nt
	ds_read_b128 v[152:155], v149
	v_mov_b32_e32 v125, v117
	v_lshl_add_u64 v[172:173], v[160:161], 0, v[124:125]
	v_lshl_add_u64 v[176:177], v[172:173], 0, v[118:119]
	ds_read_b128 v[172:175], v150 offset:4352
	s_waitcnt lgkmcnt(1)
	global_store_dwordx4 v[176:177], v[152:155], off nt
	v_mov_b32_e32 v127, v117
	s_mov_b32 s29, s27
	v_lshl_add_u64 v[152:153], v[160:161], 0, s[2:3]
	v_lshl_add_u64 v[154:155], v[152:153], 0, v[116:117]
	v_lshl_add_u64 v[154:155], v[154:155], 0, v[118:119]
	global_store_dwordx4 v[154:155], v[156:159], off nt
	v_lshl_add_u64 v[154:155], v[152:153], 0, v[120:121]
	v_lshl_add_u64 v[154:155], v[154:155], 0, v[118:119]
	global_store_dwordx4 v[154:155], v[164:167], off nt
	v_lshl_add_u64 v[154:155], v[152:153], 0, v[122:123]
	v_lshl_add_u64 v[152:153], v[152:153], 0, v[126:127]
	v_lshl_add_u64 v[154:155], v[154:155], 0, v[118:119]
	v_lshl_add_u64 v[152:153], v[152:153], 0, v[118:119]
	global_store_dwordx4 v[154:155], v[168:171], off nt
	s_waitcnt lgkmcnt(0)
	global_store_dwordx4 v[152:153], v[172:175], off nt
	s_cbranch_vccz .LBB0_328

.LBB0_356:
	v_readfirstlane_b32 s96, v158
	v_readfirstlane_b32 s97, v159
	v_and_b32_e32 v254, 63, v162
	v_lshlrev_b32_e32 v254, 4, v254
	s_add_u32 s98, s96, 0x3000
	s_addc_u32 s99, s97, 0
	s_add_u32 s96, s96, 0x1000
	s_addc_u32 s97, s97, 0
	v_mov_b32_e32 v218, v68
	v_mov_b32_e32 v216, v163
	v_ashrrev_i32_e32 v217, 31, v163
	v_lshl_add_u64 v[216:217], v[216:217], 2, s[38:39]
	global_load_dword v204, v[216:217], off
	global_load_dword v205, v[216:217], off offset:128
	global_load_dword v206, v[216:217], off offset:256
	global_load_dword v207, v[216:217], off offset:384
	global_load_dwordx4 v[106:109], v254, s[96:97] offset:-4096
	global_load_dwordx4 v[110:113], v254, s[96:97] offset:-3072
	global_load_dwordx4 v[114:117], v254, s[96:97] offset:-2048
	global_load_dwordx4 v[118:121], v254, s[96:97] offset:-1024
	global_load_dwordx4 v[122:125], v254, s[96:97] offset:0
	global_load_dwordx4 v[126:129], v254, s[96:97] offset:1024
	global_load_dwordx4 v[130:133], v254, s[96:97] offset:2048
	global_load_dwordx4 v[134:137], v254, s[96:97] offset:3072
	global_load_dwordx4 v[138:141], v254, s[98:99] offset:-4096
	global_load_dwordx4 v[142:145], v254, s[98:99] offset:-3072
	global_load_dwordx4 v[146:149], v254, s[98:99] offset:-2048
	global_load_dwordx4 v[150:153], v254, s[98:99] offset:-1024
	global_load_dwordx4 v[154:157], v254, s[98:99] offset:0
	global_load_dwordx4 v[176:179], v254, s[98:99] offset:1024
	global_load_dwordx4 v[180:183], v254, s[98:99] offset:2048
	global_load_dwordx4 v[184:187], v254, s[98:99] offset:3072
	ds_read_b128 v[66:69], v218
	ds_read_b128 v[70:73], v218 offset:32
	ds_read_b128 v[74:77], v218 offset:64
	ds_read_b128 v[78:81], v218 offset:96
	s_add_u32 s100, s92, s20
	s_addc_u32 s101, s93, s21
	s_add_u32 s100, s100, 0x2e400000
	s_addc_u32 s101, s101, 0
	v_xor_b32_e32 v208, 16, v174
	v_lshlrev_b32_e32 v208, 2, v208
	s_waitcnt lgkmcnt(0)
	v_rcp_f32_e32 v66, v66
	v_rcp_f32_e32 v67, v67
	v_rcp_f32_e32 v68, v68
	v_rcp_f32_e32 v69, v69
	v_rcp_f32_e32 v70, v70
	v_rcp_f32_e32 v71, v71
	v_rcp_f32_e32 v72, v72
	v_rcp_f32_e32 v73, v73
	v_rcp_f32_e32 v74, v74
	v_rcp_f32_e32 v75, v75
	v_rcp_f32_e32 v76, v76
	v_rcp_f32_e32 v77, v77
	v_rcp_f32_e32 v78, v78
	v_rcp_f32_e32 v79, v79
	v_rcp_f32_e32 v80, v80
	v_rcp_f32_e32 v81, v81
	v_mul_f32_e32 v66, v1, v66
	v_mul_f32_e32 v67, v1, v67
	v_mul_f32_e32 v68, v1, v68
	v_mul_f32_e32 v69, v1, v69
	v_mul_f32_e32 v70, v1, v70
	v_mul_f32_e32 v71, v1, v71
	v_mul_f32_e32 v72, v1, v72
	v_mul_f32_e32 v73, v1, v73
	v_mul_f32_e32 v74, v1, v74
	v_mul_f32_e32 v75, v1, v75
	v_mul_f32_e32 v76, v1, v76
	v_mul_f32_e32 v77, v1, v77
	v_mul_f32_e32 v78, v1, v78
	v_mul_f32_e32 v79, v1, v79
	v_mul_f32_e32 v80, v1, v80
	v_mul_f32_e32 v81, v1, v81
	s_waitcnt vmcnt(15)
	v_fma_f32 v106, -v50, v66, v106
	v_fma_f32 v107, -v34, v66, v107
	v_fma_f32 v108, -v18, v66, v108
	v_fma_f32 v109, -v2, v66, v109
	v_mul_f32_e32 v204, 0x3f4ccccd, v204
	v_mul_f32_e32 v205, 0x3f4ccccd, v205
	v_mul_f32_e32 v206, 0x3f4ccccd, v206
	v_mul_f32_e32 v207, 0x3f4ccccd, v207
	v_mul_f32_e32 v66, v106, v106
	v_fmac_f32_e32 v66, v107, v107
	v_fmac_f32_e32 v66, v108, v108
	v_fmac_f32_e32 v66, v109, v109
	s_waitcnt vmcnt(14)
	v_fma_f32 v110, -v51, v67, v110
	v_fma_f32 v111, -v35, v67, v111
	v_fma_f32 v112, -v19, v67, v112
	v_fma_f32 v113, -v3, v67, v113
	v_mul_f32_e32 v67, v110, v110
	v_fmac_f32_e32 v67, v111, v111
	v_fmac_f32_e32 v67, v112, v112
	v_fmac_f32_e32 v67, v113, v113
	s_waitcnt vmcnt(13)
	v_fma_f32 v114, -v52, v68, v114
	v_fma_f32 v115, -v36, v68, v115
	v_fma_f32 v116, -v20, v68, v116
	v_fma_f32 v117, -v4, v68, v117
	v_mul_f32_e32 v68, v114, v114
	v_fmac_f32_e32 v68, v115, v115
	v_fmac_f32_e32 v68, v116, v116
	v_fmac_f32_e32 v68, v117, v117
	s_waitcnt vmcnt(12)
	v_fma_f32 v118, -v53, v69, v118
	v_fma_f32 v119, -v37, v69, v119
	v_fma_f32 v120, -v21, v69, v120
	v_fma_f32 v121, -v5, v69, v121
	v_mul_f32_e32 v69, v118, v118
	v_fmac_f32_e32 v69, v119, v119
	v_fmac_f32_e32 v69, v120, v120
	v_fmac_f32_e32 v69, v121, v121
	s_waitcnt vmcnt(11)
	v_fma_f32 v122, -v54, v70, v122
	v_fma_f32 v123, -v38, v70, v123
	v_fma_f32 v124, -v22, v70, v124
	v_fma_f32 v125, -v6, v70, v125
	v_mul_f32_e32 v70, v122, v122
	v_fmac_f32_e32 v70, v123, v123
	v_fmac_f32_e32 v70, v124, v124
	v_fmac_f32_e32 v70, v125, v125
	s_waitcnt vmcnt(10)
	v_fma_f32 v126, -v55, v71, v126
	v_fma_f32 v127, -v39, v71, v127
	v_fma_f32 v128, -v23, v71, v128
	v_fma_f32 v129, -v7, v71, v129
	v_mul_f32_e32 v71, v126, v126
	v_fmac_f32_e32 v71, v127, v127
	v_fmac_f32_e32 v71, v128, v128
	v_fmac_f32_e32 v71, v129, v129
	s_waitcnt vmcnt(9)
	v_fma_f32 v130, -v56, v72, v130
	v_fma_f32 v131, -v40, v72, v131
	v_fma_f32 v132, -v24, v72, v132
	v_fma_f32 v133, -v8, v72, v133
	v_mul_f32_e32 v72, v130, v130
	v_fmac_f32_e32 v72, v131, v131
	v_fmac_f32_e32 v72, v132, v132
	v_fmac_f32_e32 v72, v133, v133
	s_waitcnt vmcnt(8)
	v_fma_f32 v134, -v57, v73, v134
	v_fma_f32 v135, -v41, v73, v135
	v_fma_f32 v136, -v25, v73, v136
	v_fma_f32 v137, -v9, v73, v137
	v_mul_f32_e32 v73, v134, v134
	v_fmac_f32_e32 v73, v135, v135
	v_fmac_f32_e32 v73, v136, v136
	v_fmac_f32_e32 v73, v137, v137
	s_waitcnt vmcnt(7)
	v_fma_f32 v138, -v58, v74, v138
	v_fma_f32 v139, -v42, v74, v139
	v_fma_f32 v140, -v26, v74, v140
	v_fma_f32 v141, -v10, v74, v141
	v_mul_f32_e32 v74, v138, v138
	v_fmac_f32_e32 v74, v139, v139
	v_fmac_f32_e32 v74, v140, v140
	v_fmac_f32_e32 v74, v141, v141
	s_waitcnt vmcnt(6)
	v_fma_f32 v142, -v59, v75, v142
	v_fma_f32 v143, -v43, v75, v143
	v_fma_f32 v144, -v27, v75, v144
	v_fma_f32 v145, -v11, v75, v145
	v_mul_f32_e32 v75, v142, v142
	v_fmac_f32_e32 v75, v143, v143
	v_fmac_f32_e32 v75, v144, v144
	v_fmac_f32_e32 v75, v145, v145
	s_waitcnt vmcnt(5)
	v_fma_f32 v146, -v60, v76, v146
	v_fma_f32 v147, -v44, v76, v147
	v_fma_f32 v148, -v28, v76, v148
	v_fma_f32 v149, -v12, v76, v149
	v_mul_f32_e32 v76, v146, v146
	v_fmac_f32_e32 v76, v147, v147
	v_fmac_f32_e32 v76, v148, v148
	v_fmac_f32_e32 v76, v149, v149
	s_waitcnt vmcnt(4)
	v_fma_f32 v150, -v61, v77, v150
	v_fma_f32 v151, -v45, v77, v151
	v_fma_f32 v152, -v29, v77, v152
	v_fma_f32 v153, -v13, v77, v153
	v_mul_f32_e32 v77, v150, v150
	v_fmac_f32_e32 v77, v151, v151
	v_fmac_f32_e32 v77, v152, v152
	v_fmac_f32_e32 v77, v153, v153
	s_waitcnt vmcnt(3)
	v_fma_f32 v154, -v62, v78, v154
	v_fma_f32 v155, -v46, v78, v155
	v_fma_f32 v156, -v30, v78, v156
	v_fma_f32 v157, -v14, v78, v157
	v_mul_f32_e32 v78, v154, v154
	v_fmac_f32_e32 v78, v155, v155
	v_fmac_f32_e32 v78, v156, v156
	v_fmac_f32_e32 v78, v157, v157
	s_waitcnt vmcnt(2)
	v_fma_f32 v176, -v63, v79, v176
	v_fma_f32 v177, -v47, v79, v177
	v_fma_f32 v178, -v31, v79, v178
	v_fma_f32 v179, -v15, v79, v179
	v_mul_f32_e32 v79, v176, v176
	v_fmac_f32_e32 v79, v177, v177
	v_fmac_f32_e32 v79, v178, v178
	v_fmac_f32_e32 v79, v179, v179
	s_waitcnt vmcnt(1)
	v_fma_f32 v180, -v64, v80, v180
	v_fma_f32 v181, -v48, v80, v181
	v_fma_f32 v182, -v32, v80, v182
	v_fma_f32 v183, -v16, v80, v183
	v_mul_f32_e32 v80, v180, v180
	v_fmac_f32_e32 v80, v181, v181
	v_fmac_f32_e32 v80, v182, v182
	v_fmac_f32_e32 v80, v183, v183
	s_waitcnt vmcnt(0)
	v_fma_f32 v184, -v65, v81, v184
	v_fma_f32 v185, -v49, v81, v185
	v_fma_f32 v186, -v33, v81, v186
	v_fma_f32 v187, -v17, v81, v187
	v_mul_f32_e32 v81, v184, v184
	v_fmac_f32_e32 v81, v185, v185
	v_fmac_f32_e32 v81, v186, v186
	v_fmac_f32_e32 v81, v187, v187
	v_add_f32_dpp v66, v66, v66 quad_perm:[1,0,3,2] row_mask:0xf bank_mask:0xf
	v_add_f32_dpp v67, v67, v67 quad_perm:[1,0,3,2] row_mask:0xf bank_mask:0xf
	v_add_f32_dpp v68, v68, v68 quad_perm:[1,0,3,2] row_mask:0xf bank_mask:0xf
	v_add_f32_dpp v69, v69, v69 quad_perm:[1,0,3,2] row_mask:0xf bank_mask:0xf
	v_add_f32_dpp v70, v70, v70 quad_perm:[1,0,3,2] row_mask:0xf bank_mask:0xf
	v_add_f32_dpp v71, v71, v71 quad_perm:[1,0,3,2] row_mask:0xf bank_mask:0xf
	v_add_f32_dpp v72, v72, v72 quad_perm:[1,0,3,2] row_mask:0xf bank_mask:0xf
	v_add_f32_dpp v73, v73, v73 quad_perm:[1,0,3,2] row_mask:0xf bank_mask:0xf
	v_add_f32_dpp v74, v74, v74 quad_perm:[1,0,3,2] row_mask:0xf bank_mask:0xf
	v_add_f32_dpp v75, v75, v75 quad_perm:[1,0,3,2] row_mask:0xf bank_mask:0xf
	v_add_f32_dpp v76, v76, v76 quad_perm:[1,0,3,2] row_mask:0xf bank_mask:0xf
	v_add_f32_dpp v77, v77, v77 quad_perm:[1,0,3,2] row_mask:0xf bank_mask:0xf
	v_add_f32_dpp v78, v78, v78 quad_perm:[1,0,3,2] row_mask:0xf bank_mask:0xf
	v_add_f32_dpp v79, v79, v79 quad_perm:[1,0,3,2] row_mask:0xf bank_mask:0xf
	v_add_f32_dpp v80, v80, v80 quad_perm:[1,0,3,2] row_mask:0xf bank_mask:0xf
	v_add_f32_dpp v81, v81, v81 quad_perm:[1,0,3,2] row_mask:0xf bank_mask:0xf
	v_add_f32_dpp v66, v66, v66 quad_perm:[2,3,0,1] row_mask:0xf bank_mask:0xf
	v_add_f32_dpp v67, v67, v67 quad_perm:[2,3,0,1] row_mask:0xf bank_mask:0xf
	v_add_f32_dpp v68, v68, v68 quad_perm:[2,3,0,1] row_mask:0xf bank_mask:0xf
	v_add_f32_dpp v69, v69, v69 quad_perm:[2,3,0,1] row_mask:0xf bank_mask:0xf
	v_add_f32_dpp v70, v70, v70 quad_perm:[2,3,0,1] row_mask:0xf bank_mask:0xf
	v_add_f32_dpp v71, v71, v71 quad_perm:[2,3,0,1] row_mask:0xf bank_mask:0xf
	v_add_f32_dpp v72, v72, v72 quad_perm:[2,3,0,1] row_mask:0xf bank_mask:0xf
	v_add_f32_dpp v73, v73, v73 quad_perm:[2,3,0,1] row_mask:0xf bank_mask:0xf
	v_add_f32_dpp v74, v74, v74 quad_perm:[2,3,0,1] row_mask:0xf bank_mask:0xf
	v_add_f32_dpp v75, v75, v75 quad_perm:[2,3,0,1] row_mask:0xf bank_mask:0xf
	v_add_f32_dpp v76, v76, v76 quad_perm:[2,3,0,1] row_mask:0xf bank_mask:0xf
	v_add_f32_dpp v77, v77, v77 quad_perm:[2,3,0,1] row_mask:0xf bank_mask:0xf
	v_add_f32_dpp v78, v78, v78 quad_perm:[2,3,0,1] row_mask:0xf bank_mask:0xf
	v_add_f32_dpp v79, v79, v79 quad_perm:[2,3,0,1] row_mask:0xf bank_mask:0xf
	v_add_f32_dpp v80, v80, v80 quad_perm:[2,3,0,1] row_mask:0xf bank_mask:0xf
	v_add_f32_dpp v81, v81, v81 quad_perm:[2,3,0,1] row_mask:0xf bank_mask:0xf
	v_add_f32_dpp v66, v66, v66 row_half_mirror row_mask:0xf bank_mask:0xf
	v_add_f32_dpp v67, v67, v67 row_half_mirror row_mask:0xf bank_mask:0xf
	v_add_f32_dpp v68, v68, v68 row_half_mirror row_mask:0xf bank_mask:0xf
	v_add_f32_dpp v69, v69, v69 row_half_mirror row_mask:0xf bank_mask:0xf
	v_add_f32_dpp v70, v70, v70 row_half_mirror row_mask:0xf bank_mask:0xf
	v_add_f32_dpp v71, v71, v71 row_half_mirror row_mask:0xf bank_mask:0xf
	v_add_f32_dpp v72, v72, v72 row_half_mirror row_mask:0xf bank_mask:0xf
	v_add_f32_dpp v73, v73, v73 row_half_mirror row_mask:0xf bank_mask:0xf
	v_add_f32_dpp v74, v74, v74 row_half_mirror row_mask:0xf bank_mask:0xf
	v_add_f32_dpp v75, v75, v75 row_half_mirror row_mask:0xf bank_mask:0xf
	v_add_f32_dpp v76, v76, v76 row_half_mirror row_mask:0xf bank_mask:0xf
	v_add_f32_dpp v77, v77, v77 row_half_mirror row_mask:0xf bank_mask:0xf
	v_add_f32_dpp v78, v78, v78 row_half_mirror row_mask:0xf bank_mask:0xf
	v_add_f32_dpp v79, v79, v79 row_half_mirror row_mask:0xf bank_mask:0xf
	v_add_f32_dpp v80, v80, v80 row_half_mirror row_mask:0xf bank_mask:0xf
	v_add_f32_dpp v81, v81, v81 row_half_mirror row_mask:0xf bank_mask:0xf
	v_add_f32_dpp v66, v66, v66 row_mirror row_mask:0xf bank_mask:0xf
	v_add_f32_dpp v67, v67, v67 row_mirror row_mask:0xf bank_mask:0xf
	v_add_f32_dpp v68, v68, v68 row_mirror row_mask:0xf bank_mask:0xf
	v_add_f32_dpp v69, v69, v69 row_mirror row_mask:0xf bank_mask:0xf
	v_add_f32_dpp v70, v70, v70 row_mirror row_mask:0xf bank_mask:0xf
	v_add_f32_dpp v71, v71, v71 row_mirror row_mask:0xf bank_mask:0xf
	v_add_f32_dpp v72, v72, v72 row_mirror row_mask:0xf bank_mask:0xf
	v_add_f32_dpp v73, v73, v73 row_mirror row_mask:0xf bank_mask:0xf
	v_add_f32_dpp v74, v74, v74 row_mirror row_mask:0xf bank_mask:0xf
	v_add_f32_dpp v75, v75, v75 row_mirror row_mask:0xf bank_mask:0xf
	v_add_f32_dpp v76, v76, v76 row_mirror row_mask:0xf bank_mask:0xf
	v_add_f32_dpp v77, v77, v77 row_mirror row_mask:0xf bank_mask:0xf
	v_add_f32_dpp v78, v78, v78 row_mirror row_mask:0xf bank_mask:0xf
	v_add_f32_dpp v79, v79, v79 row_mirror row_mask:0xf bank_mask:0xf
	v_add_f32_dpp v80, v80, v80 row_mirror row_mask:0xf bank_mask:0xf
	v_add_f32_dpp v81, v81, v81 row_mirror row_mask:0xf bank_mask:0xf
	ds_bpermute_b32 v188, v208, v66
	ds_bpermute_b32 v189, v208, v67
	ds_bpermute_b32 v190, v208, v68
	ds_bpermute_b32 v191, v208, v69
	ds_bpermute_b32 v192, v208, v70
	ds_bpermute_b32 v193, v208, v71
	ds_bpermute_b32 v194, v208, v72
	ds_bpermute_b32 v195, v208, v73
	ds_bpermute_b32 v196, v208, v74
	ds_bpermute_b32 v197, v208, v75
	ds_bpermute_b32 v198, v208, v76
	ds_bpermute_b32 v199, v208, v77
	ds_bpermute_b32 v200, v208, v78
	ds_bpermute_b32 v201, v208, v79
	ds_bpermute_b32 v202, v208, v80
	ds_bpermute_b32 v203, v208, v81
	s_waitcnt lgkmcnt(0)
	v_add_f32_e32 v66, v66, v188
	v_add_f32_e32 v67, v67, v189
	v_add_f32_e32 v68, v68, v190
	v_add_f32_e32 v69, v69, v191
	v_add_f32_e32 v70, v70, v192
	v_add_f32_e32 v71, v71, v193
	v_add_f32_e32 v72, v72, v194
	v_add_f32_e32 v73, v73, v195
	v_add_f32_e32 v74, v74, v196
	v_add_f32_e32 v75, v75, v197
	v_add_f32_e32 v76, v76, v198
	v_add_f32_e32 v77, v77, v199
	v_add_f32_e32 v78, v78, v200
	v_add_f32_e32 v79, v79, v201
	v_add_f32_e32 v80, v80, v202
	v_add_f32_e32 v81, v81, v203
	v_fmamk_f32 v66, v66, 0x3c000000, v172
	v_fmamk_f32 v67, v67, 0x3c000000, v172
	v_fmamk_f32 v68, v68, 0x3c000000, v172
	v_fmamk_f32 v69, v69, 0x3c000000, v172
	v_fmamk_f32 v70, v70, 0x3c000000, v172
	v_fmamk_f32 v71, v71, 0x3c000000, v172
	v_fmamk_f32 v72, v72, 0x3c000000, v172
	v_fmamk_f32 v73, v73, 0x3c000000, v172
	v_fmamk_f32 v74, v74, 0x3c000000, v172
	v_fmamk_f32 v75, v75, 0x3c000000, v172
	v_fmamk_f32 v76, v76, 0x3c000000, v172
	v_fmamk_f32 v77, v77, 0x3c000000, v172
	v_fmamk_f32 v78, v78, 0x3c000000, v172
	v_fmamk_f32 v79, v79, 0x3c000000, v172
	v_fmamk_f32 v80, v80, 0x3c000000, v172
	v_fmamk_f32 v81, v81, 0x3c000000, v172
	v_rsq_f32_e32 v66, v66
	v_rsq_f32_e32 v67, v67
	v_rsq_f32_e32 v68, v68
	v_rsq_f32_e32 v69, v69
	v_rsq_f32_e32 v70, v70
	v_rsq_f32_e32 v71, v71
	v_rsq_f32_e32 v72, v72
	v_rsq_f32_e32 v73, v73
	v_rsq_f32_e32 v74, v74
	v_rsq_f32_e32 v75, v75
	v_rsq_f32_e32 v76, v76
	v_rsq_f32_e32 v77, v77
	v_rsq_f32_e32 v78, v78
	v_rsq_f32_e32 v79, v79
	v_rsq_f32_e32 v80, v80
	v_rsq_f32_e32 v81, v81
	s_nop 0
	s_mov_b32 s96, 0xaaaaaaaa
	s_mov_b32 s97, 0xaaaaaaaa
	s_mov_b32 s98, 0xcccccccc
	s_mov_b32 s99, 0xcccccccc
	v_mov_b32_e32 v202, 0x5040100
	v_mov_b32_e32 v203, 0x3020706
	v_cndmask_b32_e64 v202, v202, v203, s[96:97]
	v_and_b32_e32 v209, 3, v163
	v_lshl_add_u32 v209, v164, 2, v209
	v_add_u32_e32 v209, v175, v209
	v_lshlrev_b32_e32 v209, 12, v209
	v_lshrrev_b32_e32 v210, 2, v163
	v_lshl_add_u32 v209, v210, 3, v209
	v_mul_f32_e32 v198, v106, v66
	v_mul_f32_e32 v199, v110, v67
	v_mul_f32_e32 v200, v114, v68
	v_mul_f32_e32 v201, v118, v69
	v_mul_f32_e32 v198, v204, v198
	v_mul_f32_e32 v199, v204, v199
	v_mul_f32_e32 v200, v204, v200
	v_mul_f32_e32 v201, v204, v201
	v_cvt_pk_bf16_f32 v188, v198, v199
	v_cvt_pk_bf16_f32 v189, v200, v201
	s_nop 0
	v_mov_b32_dpp v190, v188 quad_perm:[1,0,3,2] row_mask:0xf bank_mask:0xf
	v_mov_b32_dpp v191, v189 quad_perm:[1,0,3,2] row_mask:0xf bank_mask:0xf
	v_perm_b32 v192, v190, v188, v202
	v_perm_b32 v193, v191, v189, v202
	v_cndmask_b32_e64 v194, v193, v192, s[98:99]
	s_nop 1
	v_mov_b32_dpp v195, v194 quad_perm:[2,3,0,1] row_mask:0xf bank_mask:0xf
	v_cndmask_b32_e64 v196, v192, v195, s[98:99]
	v_cndmask_b32_e64 v197, v195, v193, s[98:99]
	global_store_dwordx2 v209, v[196:197], s[100:101] offset:2048 nt
	v_mul_f32_e32 v198, v107, v66
	v_mul_f32_e32 v199, v111, v67
	v_mul_f32_e32 v200, v115, v68
	v_mul_f32_e32 v201, v119, v69
	v_mul_f32_e32 v198, v205, v198
	v_mul_f32_e32 v199, v205, v199
	v_mul_f32_e32 v200, v205, v200
	v_mul_f32_e32 v201, v205, v201
	v_cvt_pk_bf16_f32 v188, v198, v199
	v_cvt_pk_bf16_f32 v189, v200, v201
	s_nop 0
	v_mov_b32_dpp v190, v188 quad_perm:[1,0,3,2] row_mask:0xf bank_mask:0xf
	v_mov_b32_dpp v191, v189 quad_perm:[1,0,3,2] row_mask:0xf bank_mask:0xf
	v_perm_b32 v192, v190, v188, v202
	v_perm_b32 v193, v191, v189, v202
	v_cndmask_b32_e64 v194, v193, v192, s[98:99]
	s_nop 1
	v_mov_b32_dpp v195, v194 quad_perm:[2,3,0,1] row_mask:0xf bank_mask:0xf
	v_cndmask_b32_e64 v216, v192, v195, s[98:99]
	v_cndmask_b32_e64 v217, v195, v193, s[98:99]
	global_store_dwordx2 v209, v[216:217], s[100:101] offset:2112 nt
	v_mul_f32_e32 v198, v108, v66
	v_mul_f32_e32 v199, v112, v67
	v_mul_f32_e32 v200, v116, v68
	v_mul_f32_e32 v201, v120, v69
	v_mul_f32_e32 v198, v206, v198
	v_mul_f32_e32 v199, v206, v199
	v_mul_f32_e32 v200, v206, v200
	v_mul_f32_e32 v201, v206, v201
	v_cvt_pk_bf16_f32 v188, v198, v199
	v_cvt_pk_bf16_f32 v189, v200, v201
	s_nop 0
	v_mov_b32_dpp v190, v188 quad_perm:[1,0,3,2] row_mask:0xf bank_mask:0xf
	v_mov_b32_dpp v191, v189 quad_perm:[1,0,3,2] row_mask:0xf bank_mask:0xf
	v_perm_b32 v192, v190, v188, v202
	v_perm_b32 v193, v191, v189, v202
	v_cndmask_b32_e64 v194, v193, v192, s[98:99]
	s_nop 1
	v_mov_b32_dpp v195, v194 quad_perm:[2,3,0,1] row_mask:0xf bank_mask:0xf
	v_cndmask_b32_e64 v196, v192, v195, s[98:99]
	v_cndmask_b32_e64 v197, v195, v193, s[98:99]
	global_store_dwordx2 v209, v[196:197], s[100:101] offset:2176 nt
	v_mul_f32_e32 v198, v109, v66
	v_mul_f32_e32 v199, v113, v67
	v_mul_f32_e32 v200, v117, v68
	v_mul_f32_e32 v201, v121, v69
	v_mul_f32_e32 v198, v207, v198
	v_mul_f32_e32 v199, v207, v199
	v_mul_f32_e32 v200, v207, v200
	v_mul_f32_e32 v201, v207, v201
	v_cvt_pk_bf16_f32 v188, v198, v199
	v_cvt_pk_bf16_f32 v189, v200, v201
	s_nop 0
	v_mov_b32_dpp v190, v188 quad_perm:[1,0,3,2] row_mask:0xf bank_mask:0xf
	v_mov_b32_dpp v191, v189 quad_perm:[1,0,3,2] row_mask:0xf bank_mask:0xf
	v_perm_b32 v192, v190, v188, v202
	v_perm_b32 v193, v191, v189, v202
	v_cndmask_b32_e64 v194, v193, v192, s[98:99]
	s_nop 1
	v_mov_b32_dpp v195, v194 quad_perm:[2,3,0,1] row_mask:0xf bank_mask:0xf
	v_cndmask_b32_e64 v216, v192, v195, s[98:99]
	v_cndmask_b32_e64 v217, v195, v193, s[98:99]
	global_store_dwordx2 v209, v[216:217], s[100:101] offset:2240 nt
	v_add_u32_e32 v210, 0x8000, v209
	v_mul_f32_e32 v198, v122, v70
	v_mul_f32_e32 v199, v126, v71
	v_mul_f32_e32 v200, v130, v72
	v_mul_f32_e32 v201, v134, v73
	v_mul_f32_e32 v198, v204, v198
	v_mul_f32_e32 v199, v204, v199
	v_mul_f32_e32 v200, v204, v200
	v_mul_f32_e32 v201, v204, v201
	v_cvt_pk_bf16_f32 v188, v198, v199
	v_cvt_pk_bf16_f32 v189, v200, v201
	s_nop 0
	v_mov_b32_dpp v190, v188 quad_perm:[1,0,3,2] row_mask:0xf bank_mask:0xf
	v_mov_b32_dpp v191, v189 quad_perm:[1,0,3,2] row_mask:0xf bank_mask:0xf
	v_perm_b32 v192, v190, v188, v202
	v_perm_b32 v193, v191, v189, v202
	v_cndmask_b32_e64 v194, v193, v192, s[98:99]
	s_nop 1
	v_mov_b32_dpp v195, v194 quad_perm:[2,3,0,1] row_mask:0xf bank_mask:0xf
	v_cndmask_b32_e64 v196, v192, v195, s[98:99]
	v_cndmask_b32_e64 v197, v195, v193, s[98:99]
	global_store_dwordx2 v210, v[196:197], s[100:101] offset:2048 nt
	v_mul_f32_e32 v198, v123, v70
	v_mul_f32_e32 v199, v127, v71
	v_mul_f32_e32 v200, v131, v72
	v_mul_f32_e32 v201, v135, v73
	v_mul_f32_e32 v198, v205, v198
	v_mul_f32_e32 v199, v205, v199
	v_mul_f32_e32 v200, v205, v200
	v_mul_f32_e32 v201, v205, v201
	v_cvt_pk_bf16_f32 v188, v198, v199
	v_cvt_pk_bf16_f32 v189, v200, v201
	s_nop 0
	v_mov_b32_dpp v190, v188 quad_perm:[1,0,3,2] row_mask:0xf bank_mask:0xf
	v_mov_b32_dpp v191, v189 quad_perm:[1,0,3,2] row_mask:0xf bank_mask:0xf
	v_perm_b32 v192, v190, v188, v202
	v_perm_b32 v193, v191, v189, v202
	v_cndmask_b32_e64 v194, v193, v192, s[98:99]
	s_nop 1
	v_mov_b32_dpp v195, v194 quad_perm:[2,3,0,1] row_mask:0xf bank_mask:0xf
	v_cndmask_b32_e64 v216, v192, v195, s[98:99]
	v_cndmask_b32_e64 v217, v195, v193, s[98:99]
	global_store_dwordx2 v210, v[216:217], s[100:101] offset:2112 nt
	v_mul_f32_e32 v198, v124, v70
	v_mul_f32_e32 v199, v128, v71
	v_mul_f32_e32 v200, v132, v72
	v_mul_f32_e32 v201, v136, v73
	v_mul_f32_e32 v198, v206, v198
	v_mul_f32_e32 v199, v206, v199
	v_mul_f32_e32 v200, v206, v200
	v_mul_f32_e32 v201, v206, v201
	v_cvt_pk_bf16_f32 v188, v198, v199
	v_cvt_pk_bf16_f32 v189, v200, v201
	s_nop 0
	v_mov_b32_dpp v190, v188 quad_perm:[1,0,3,2] row_mask:0xf bank_mask:0xf
	v_mov_b32_dpp v191, v189 quad_perm:[1,0,3,2] row_mask:0xf bank_mask:0xf
	v_perm_b32 v192, v190, v188, v202
	v_perm_b32 v193, v191, v189, v202
	v_cndmask_b32_e64 v194, v193, v192, s[98:99]
	s_nop 1
	v_mov_b32_dpp v195, v194 quad_perm:[2,3,0,1] row_mask:0xf bank_mask:0xf
	v_cndmask_b32_e64 v196, v192, v195, s[98:99]
	v_cndmask_b32_e64 v197, v195, v193, s[98:99]
	global_store_dwordx2 v210, v[196:197], s[100:101] offset:2176 nt
	v_mul_f32_e32 v198, v125, v70
	v_mul_f32_e32 v199, v129, v71
	v_mul_f32_e32 v200, v133, v72
	v_mul_f32_e32 v201, v137, v73
	v_mul_f32_e32 v198, v207, v198
	v_mul_f32_e32 v199, v207, v199
	v_mul_f32_e32 v200, v207, v200
	v_mul_f32_e32 v201, v207, v201
	v_cvt_pk_bf16_f32 v188, v198, v199
	v_cvt_pk_bf16_f32 v189, v200, v201
	s_nop 0
	v_mov_b32_dpp v190, v188 quad_perm:[1,0,3,2] row_mask:0xf bank_mask:0xf
	v_mov_b32_dpp v191, v189 quad_perm:[1,0,3,2] row_mask:0xf bank_mask:0xf
	v_perm_b32 v192, v190, v188, v202
	v_perm_b32 v193, v191, v189, v202
	v_cndmask_b32_e64 v194, v193, v192, s[98:99]
	s_nop 1
	v_mov_b32_dpp v195, v194 quad_perm:[2,3,0,1] row_mask:0xf bank_mask:0xf
	v_cndmask_b32_e64 v216, v192, v195, s[98:99]
	v_cndmask_b32_e64 v217, v195, v193, s[98:99]
	global_store_dwordx2 v210, v[216:217], s[100:101] offset:2240 nt
	v_add_u32_e32 v210, 0x10000, v209
	v_mul_f32_e32 v198, v138, v74
	v_mul_f32_e32 v199, v142, v75
	v_mul_f32_e32 v200, v146, v76
	v_mul_f32_e32 v201, v150, v77
	v_mul_f32_e32 v198, v204, v198
	v_mul_f32_e32 v199, v204, v199
	v_mul_f32_e32 v200, v204, v200
	v_mul_f32_e32 v201, v204, v201
	v_cvt_pk_bf16_f32 v188, v198, v199
	v_cvt_pk_bf16_f32 v189, v200, v201
	s_nop 0
	v_mov_b32_dpp v190, v188 quad_perm:[1,0,3,2] row_mask:0xf bank_mask:0xf
	v_mov_b32_dpp v191, v189 quad_perm:[1,0,3,2] row_mask:0xf bank_mask:0xf
	v_perm_b32 v192, v190, v188, v202
	v_perm_b32 v193, v191, v189, v202
	v_cndmask_b32_e64 v194, v193, v192, s[98:99]
	s_nop 1
	v_mov_b32_dpp v195, v194 quad_perm:[2,3,0,1] row_mask:0xf bank_mask:0xf
	v_cndmask_b32_e64 v196, v192, v195, s[98:99]
	v_cndmask_b32_e64 v197, v195, v193, s[98:99]
	global_store_dwordx2 v210, v[196:197], s[100:101] offset:2048 nt
	v_mul_f32_e32 v198, v139, v74
	v_mul_f32_e32 v199, v143, v75
	v_mul_f32_e32 v200, v147, v76
	v_mul_f32_e32 v201, v151, v77
	v_mul_f32_e32 v198, v205, v198
	v_mul_f32_e32 v199, v205, v199
	v_mul_f32_e32 v200, v205, v200
	v_mul_f32_e32 v201, v205, v201
	v_cvt_pk_bf16_f32 v188, v198, v199
	v_cvt_pk_bf16_f32 v189, v200, v201
	s_nop 0
	v_mov_b32_dpp v190, v188 quad_perm:[1,0,3,2] row_mask:0xf bank_mask:0xf
	v_mov_b32_dpp v191, v189 quad_perm:[1,0,3,2] row_mask:0xf bank_mask:0xf
	v_perm_b32 v192, v190, v188, v202
	v_perm_b32 v193, v191, v189, v202
	v_cndmask_b32_e64 v194, v193, v192, s[98:99]
	s_nop 1
	v_mov_b32_dpp v195, v194 quad_perm:[2,3,0,1] row_mask:0xf bank_mask:0xf
	v_cndmask_b32_e64 v216, v192, v195, s[98:99]
	v_cndmask_b32_e64 v217, v195, v193, s[98:99]
	global_store_dwordx2 v210, v[216:217], s[100:101] offset:2112 nt
	v_mul_f32_e32 v198, v140, v74
	v_mul_f32_e32 v199, v144, v75
	v_mul_f32_e32 v200, v148, v76
	v_mul_f32_e32 v201, v152, v77
	v_mul_f32_e32 v198, v206, v198
	v_mul_f32_e32 v199, v206, v199
	v_mul_f32_e32 v200, v206, v200
	v_mul_f32_e32 v201, v206, v201
	v_cvt_pk_bf16_f32 v188, v198, v199
	v_cvt_pk_bf16_f32 v189, v200, v201
	s_nop 0
	v_mov_b32_dpp v190, v188 quad_perm:[1,0,3,2] row_mask:0xf bank_mask:0xf
	v_mov_b32_dpp v191, v189 quad_perm:[1,0,3,2] row_mask:0xf bank_mask:0xf
	v_perm_b32 v192, v190, v188, v202
	v_perm_b32 v193, v191, v189, v202
	v_cndmask_b32_e64 v194, v193, v192, s[98:99]
	s_nop 1
	v_mov_b32_dpp v195, v194 quad_perm:[2,3,0,1] row_mask:0xf bank_mask:0xf
	v_cndmask_b32_e64 v196, v192, v195, s[98:99]
	v_cndmask_b32_e64 v197, v195, v193, s[98:99]
	global_store_dwordx2 v210, v[196:197], s[100:101] offset:2176 nt
	v_mul_f32_e32 v198, v141, v74
	v_mul_f32_e32 v199, v145, v75
	v_mul_f32_e32 v200, v149, v76
	v_mul_f32_e32 v201, v153, v77
	v_mul_f32_e32 v198, v207, v198
	v_mul_f32_e32 v199, v207, v199
	v_mul_f32_e32 v200, v207, v200
	v_mul_f32_e32 v201, v207, v201
	v_cvt_pk_bf16_f32 v188, v198, v199
	v_cvt_pk_bf16_f32 v189, v200, v201
	s_nop 0
	v_mov_b32_dpp v190, v188 quad_perm:[1,0,3,2] row_mask:0xf bank_mask:0xf
	v_mov_b32_dpp v191, v189 quad_perm:[1,0,3,2] row_mask:0xf bank_mask:0xf
	v_perm_b32 v192, v190, v188, v202
	v_perm_b32 v193, v191, v189, v202
	v_cndmask_b32_e64 v194, v193, v192, s[98:99]
	s_nop 1
	v_mov_b32_dpp v195, v194 quad_perm:[2,3,0,1] row_mask:0xf bank_mask:0xf
	v_cndmask_b32_e64 v216, v192, v195, s[98:99]
	v_cndmask_b32_e64 v217, v195, v193, s[98:99]
	global_store_dwordx2 v210, v[216:217], s[100:101] offset:2240 nt
	v_add_u32_e32 v210, 0x18000, v209
	v_mul_f32_e32 v198, v154, v78
	v_mul_f32_e32 v199, v176, v79
	v_mul_f32_e32 v200, v180, v80
	v_mul_f32_e32 v201, v184, v81
	v_mul_f32_e32 v198, v204, v198
	v_mul_f32_e32 v199, v204, v199
	v_mul_f32_e32 v200, v204, v200
	v_mul_f32_e32 v201, v204, v201
	v_cvt_pk_bf16_f32 v188, v198, v199
	v_cvt_pk_bf16_f32 v189, v200, v201
	s_nop 0
	v_mov_b32_dpp v190, v188 quad_perm:[1,0,3,2] row_mask:0xf bank_mask:0xf
	v_mov_b32_dpp v191, v189 quad_perm:[1,0,3,2] row_mask:0xf bank_mask:0xf
	v_perm_b32 v192, v190, v188, v202
	v_perm_b32 v193, v191, v189, v202
	v_cndmask_b32_e64 v194, v193, v192, s[98:99]
	s_nop 1
	v_mov_b32_dpp v195, v194 quad_perm:[2,3,0,1] row_mask:0xf bank_mask:0xf
	v_cndmask_b32_e64 v196, v192, v195, s[98:99]
	v_cndmask_b32_e64 v197, v195, v193, s[98:99]
	global_store_dwordx2 v210, v[196:197], s[100:101] offset:2048 nt
	v_mul_f32_e32 v198, v155, v78
	v_mul_f32_e32 v199, v177, v79
	v_mul_f32_e32 v200, v181, v80
	v_mul_f32_e32 v201, v185, v81
	v_mul_f32_e32 v198, v205, v198
	v_mul_f32_e32 v199, v205, v199
	v_mul_f32_e32 v200, v205, v200
	v_mul_f32_e32 v201, v205, v201
	v_cvt_pk_bf16_f32 v188, v198, v199
	v_cvt_pk_bf16_f32 v189, v200, v201
	s_nop 0
	v_mov_b32_dpp v190, v188 quad_perm:[1,0,3,2] row_mask:0xf bank_mask:0xf
	v_mov_b32_dpp v191, v189 quad_perm:[1,0,3,2] row_mask:0xf bank_mask:0xf
	v_perm_b32 v192, v190, v188, v202
	v_perm_b32 v193, v191, v189, v202
	v_cndmask_b32_e64 v194, v193, v192, s[98:99]
	s_nop 1
	v_mov_b32_dpp v195, v194 quad_perm:[2,3,0,1] row_mask:0xf bank_mask:0xf
	v_cndmask_b32_e64 v216, v192, v195, s[98:99]
	v_cndmask_b32_e64 v217, v195, v193, s[98:99]
	global_store_dwordx2 v210, v[216:217], s[100:101] offset:2112 nt
	v_mul_f32_e32 v198, v156, v78
	v_mul_f32_e32 v199, v178, v79
	v_mul_f32_e32 v200, v182, v80
	v_mul_f32_e32 v201, v186, v81
	v_mul_f32_e32 v198, v206, v198
	v_mul_f32_e32 v199, v206, v199
	v_mul_f32_e32 v200, v206, v200
	v_mul_f32_e32 v201, v206, v201
	v_cvt_pk_bf16_f32 v188, v198, v199
	v_cvt_pk_bf16_f32 v189, v200, v201
	s_nop 0
	v_mov_b32_dpp v190, v188 quad_perm:[1,0,3,2] row_mask:0xf bank_mask:0xf
	v_mov_b32_dpp v191, v189 quad_perm:[1,0,3,2] row_mask:0xf bank_mask:0xf
	v_perm_b32 v192, v190, v188, v202
	v_perm_b32 v193, v191, v189, v202
	v_cndmask_b32_e64 v194, v193, v192, s[98:99]
	s_nop 1
	v_mov_b32_dpp v195, v194 quad_perm:[2,3,0,1] row_mask:0xf bank_mask:0xf
	v_cndmask_b32_e64 v196, v192, v195, s[98:99]
	v_cndmask_b32_e64 v197, v195, v193, s[98:99]
	global_store_dwordx2 v210, v[196:197], s[100:101] offset:2176 nt
	v_mul_f32_e32 v198, v157, v78
	v_mul_f32_e32 v199, v179, v79
	v_mul_f32_e32 v200, v183, v80
	v_mul_f32_e32 v201, v187, v81
	v_mul_f32_e32 v198, v207, v198
	v_mul_f32_e32 v199, v207, v199
	v_mul_f32_e32 v200, v207, v200
	v_mul_f32_e32 v201, v207, v201
	v_cvt_pk_bf16_f32 v188, v198, v199
	v_cvt_pk_bf16_f32 v189, v200, v201
	s_nop 0
	v_mov_b32_dpp v190, v188 quad_perm:[1,0,3,2] row_mask:0xf bank_mask:0xf
	v_mov_b32_dpp v191, v189 quad_perm:[1,0,3,2] row_mask:0xf bank_mask:0xf
	v_perm_b32 v192, v190, v188, v202
	v_perm_b32 v193, v191, v189, v202
	v_cndmask_b32_e64 v194, v193, v192, s[98:99]
	s_nop 1
	v_mov_b32_dpp v195, v194 quad_perm:[2,3,0,1] row_mask:0xf bank_mask:0xf
	v_cndmask_b32_e64 v216, v192, v195, s[98:99]
	v_cndmask_b32_e64 v217, v195, v193, s[98:99]
	global_store_dwordx2 v210, v[216:217], s[100:101] offset:2240 nt
	s_cbranch_execnz .LBB0_335
